# hlb4: HGRN2 chunk-state item loop: barrier between an item's state MFMAs and the next item's LDS staging dropped (V image double-buffered in LDS); on top of itemwait
# speedup vs baseline: 1.0036x; 1.0027x over previous
.LBB0_420:
	s_waitcnt vmcnt(12)
	v_ashrrev_i32_e32 v30, 3, v2
	v_sub_u32_e32 v31, 63, v30
	s_lshl_b32 s8, s12, 6
	v_cndmask_b32_e64 v0, v31, v30, s[6:7]
	s_add_i32 s8, s8, s13
	v_add_u32_e32 v0, s8, v0
	v_mov_b64_e32 v[8:9], s[82:83]
	v_mad_i64_i32 v[8:9], s[8:9], v0, s85, v[8:9]
	s_lshl_b32 s8, s11, 7
	s_and_b32 s80, s8, 0x180
	v_lshlrev_b32_e32 v5, 3, v2
	s_and_b64 s[6:7], s[6:7], exec
	v_and_b32_e32 v6, 56, v5
	s_cselect_b32 s6, s90, 0xa00
	s_mov_b32 s7, s81
	v_lshl_add_u64 v[10:11], v[8:9], 0, s[80:81]
	v_lshlrev_b32_e32 v0, 1, v6
	v_lshl_add_u64 v[8:9], v[8:9], 0, s[6:7]
	v_lshl_add_u64 v[10:11], v[10:11], 0, v[0:1]
	v_lshl_add_u64 v[8:9], v[8:9], 0, s[80:81]
	v_lshl_add_u64 v[8:9], v[8:9], 0, v[0:1]
	global_load_dwordx4 v[22:25], v[10:11], off offset:3072
	global_load_dwordx4 v[18:21], v[8:9], off
	v_and_b32_e32 v3, 63, v2
	s_movk_i32 s6, 0x104
	v_mul_lo_u32 v13, v30, s6
	v_lshl_add_u32 v32, v3, 2, 0
	s_movk_i32 s6, 0x8c
	v_mad_u32_u24 v15, v3, s6, v32
	v_mov_b32_e32 v3, v1
	v_lshl_add_u64 v[8:9], v[2:3], 2, s[96:97]
	s_mov_b64 s[8:9], 0xf100000
	s_cmp_lt_i32 s10, 4
	v_add_u32_e32 v11, 0, v0
	v_lshl_add_u64 v[26:27], v[8:9], 0, s[8:9]
	s_cselect_b64 s[44:45], -1, 0
	s_and_b32 s9, s10, 1
	s_lshl_b32 s10, s10, 4
	v_add_u32_e32 v12, v11, v0
	s_and_b32 s8, s10, 0xffffffe0
	v_mov_b32_e32 v0, s10
	s_movk_i32 s10, 0xffe0
	v_bfe_u32 v10, v2, 5, 1
	v_bfi_b32 v0, s10, v0, v2
	v_mul_lo_u32 v0, v0, s89
	v_lshlrev_b32_e32 v3, 4, v10
	v_lshlrev_b32_e32 v8, 3, v10
	v_add3_u32 v34, 0, v0, v3
	v_lshrrev_b32_e32 v0, 2, v2
	v_and_or_b32 v10, v0, 3, v8
	s_lshl_b32 s10, s9, 6
	v_and_b32_e32 v0, 16, v2
	v_and_b32_e32 v7, 31, v2
	v_lshl_add_u32 v33, v2, 2, 0
	v_cmp_gt_u32_e64 s[6:7], 64, v2
	s_add_i32 s10, s10, 0
	v_lshlrev_b32_e32 v0, 1, v0
	v_and_b32_e32 v2, 24, v5
	v_add3_u32 v5, s10, v0, v2
	v_lshlrev_b32_e32 v0, 7, v7
	v_lshl_or_b32 v0, s9, 12, v0
	v_lshl_add_u64 v[2:3], s[48:49], 0, v[0:1]
	s_ashr_i32 s9, s8, 31
	v_lshl_add_u64 v[2:3], s[8:9], 1, v[2:3]
	v_mov_b32_e32 v9, v1
	s_movk_i32 s8, 0x820
	v_mul_lo_u32 v14, v30, s89
	v_lshlrev_b32_e32 v16, 4, v4
	v_lshl_add_u64 v[28:29], v[2:3], 0, v[8:9]
	v_mul_lo_u32 v2, v4, s8
	v_mul_u32_u24_e32 v3, 0x90, v10
	v_cmp_lt_i32_e64 s[8:9], 0, v4
	v_cmp_lt_i32_e64 s[10:11], 1, v4
	v_cmp_lt_i32_e64 s[12:13], 2, v4
	v_cmp_lt_i32_e64 s[14:15], 3, v4
	v_cmp_lt_i32_e64 s[16:17], 4, v4
	v_cmp_lt_i32_e64 s[18:19], 5, v4
	v_cmp_lt_i32_e64 s[20:21], 6, v4
	v_cmp_lt_i32_e64 s[22:23], 7, v4
	s_sub_i32 s35, 0x82, s51
	v_add_u32_e32 v35, v12, v13
	v_add_u32_e32 v36, v11, v14
	v_lshlrev_b32_e32 v0, 1, v6
	v_add_u32_e32 v37, v32, v2
	s_waitcnt vmcnt(6)
	v_add_u32_e32 v38, v15, v16
	v_add_u32_e32 v39, v5, v3
	s_mov_b32 s98, 0
	s_branch .LBB0_422
.LBB0_421:
	s_add_i32 s35, s35, -1
	s_andn2_b64 vcc, exec, s[46:47]
	s_mov_b32 s51, s50
	v_readlane_b32 s52, v254, 55
	s_cbranch_vccz .Lhl_exit
	s_xor_b32 s98, s98, 0x2400
	s_andn2_b64 vcc, exec, s[44:45]
	s_cbranch_vccnz .Lhl_full
	s_waitcnt vmcnt(4)
	s_branch .Lhl_body

.Lhl_body:
	v_lshlrev_b32_e32 v2, 16, v18
	v_and_b32_e32 v3, 0xffff0000, v18
	s_add_i32 s50, s51, 1
	ds_write2_b32 v35, v2, v3 offset1:1
	v_lshlrev_b32_e32 v2, 16, v19
	v_and_b32_e32 v3, 0xffff0000, v19
	s_cmp_ge_i32 s50, s34
	ds_write2_b32 v35, v2, v3 offset0:2 offset1:3
	v_lshlrev_b32_e32 v2, 16, v20
	v_and_b32_e32 v3, 0xffff0000, v20
	s_cselect_b64 s[46:47], -1, 0
	ds_write2_b32 v35, v2, v3 offset0:4 offset1:5
	v_lshlrev_b32_e32 v2, 16, v21
	v_and_b32_e32 v3, 0xffff0000, v21
	s_and_b64 vcc, exec, s[46:47]
	ds_write2_b32 v35, v2, v3 offset0:6 offset1:7
	v_add_u32_e32 v49, s98, v36
	ds_write_b128 v49, v[22:25] offset:44544
	s_cbranch_vccnz .LBB0_428
	s_mul_hi_i32 s24, s50, 0x3e0f83e1
	s_lshr_b32 s25, s24, 31
	s_ashr_i32 s52, s24, 5
	s_add_i32 s52, s52, s25
	s_mul_i32 s24, s52, 0xffffff7c
	s_add_i32 s71, s51, s24
	s_add_i32 s61, s71, 1
	s_bfe_u32 s62, s52, 0x10002
	s_cmp_lt_u32 s52, 8
	s_mul_i32 s53, s52, 0x84
	s_cselect_b64 s[24:25], -1, 0
	s_cmp_gt_i32 s61, 3
	s_mov_b64 s[48:49], -1
	s_cbranch_scc0 .LBB0_425
	s_add_i32 s63, s35, s53
	s_add_i32 s71, s71, -3
	s_and_b64 s[48:49], s[24:25], exec
	s_cselect_b32 s70, s71, s63
	s_lshl_b32 s63, s62, 13
	s_mov_b64 s[48:49], 0

.LBB0_430:
	s_or_b64 exec, exec, s[24:25]
	s_andn2_b64 vcc, exec, s[44:45]
	s_waitcnt lgkmcnt(0)
	s_barrier
	s_cbranch_vccnz .LBB0_421
	v_add_u32_e32 v49, s98, v39
	ds_read_b64_tr_b16 v[2:3], v49 offset:44544
	ds_read_b64_tr_b16 v[4:5], v49 offset:45120
	ds_read_b128 v[6:9], v34 offset:35328
	ds_read_b128 v[40:43], v34 offset:35360
	ds_read_b64_tr_b16 v[44:45], v49 offset:46848
	ds_read_b64_tr_b16 v[46:47], v49 offset:47424
	s_ashr_i32 s25, s48, 31
	s_add_u32 s24, s51, s48
	s_waitcnt lgkmcnt(3)
	v_mfma_f32_32x32x16_bf16 v[2:17], v[6:9], v[2:5], 0
	s_addc_u32 s25, s49, s25
	s_lshl_b64 s[24:25], s[24:25], 13
	s_waitcnt lgkmcnt(0)
	v_mfma_f32_32x32x16_bf16 v[2:17], v[40:43], v[44:47], v[2:17]
	ds_read_b128 v[40:43], v34 offset:35392
	ds_read_b64_tr_b16 v[44:45], v49 offset:49152
	ds_read_b64_tr_b16 v[46:47], v49 offset:49728
	s_waitcnt lgkmcnt(0)
	v_mfma_f32_32x32x16_bf16 v[2:17], v[40:43], v[44:47], v[2:17]
	ds_read_b128 v[40:43], v34 offset:35424
	ds_read_b64_tr_b16 v[44:45], v49 offset:51456
	ds_read_b64_tr_b16 v[46:47], v49 offset:52032
	s_waitcnt lgkmcnt(0)
	v_mfma_f32_32x32x16_bf16 v[2:17], v[40:43], v[44:47], v[2:17]
	v_lshl_add_u64 v[40:41], v[28:29], 0, s[24:25]
	s_nop 10
	v_cvt_pk_bf16_f32 v2, v2, v3
	v_cvt_pk_bf16_f32 v3, v4, v5
	global_store_dwordx2 v[40:41], v[2:3], off
	v_cvt_pk_bf16_f32 v2, v6, v7
	v_cvt_pk_bf16_f32 v3, v8, v9
	global_store_dwordx2 v[40:41], v[2:3], off offset:16
	v_cvt_pk_bf16_f32 v2, v10, v11
	v_cvt_pk_bf16_f32 v3, v12, v13
	global_store_dwordx2 v[40:41], v[2:3], off offset:32
	v_cvt_pk_bf16_f32 v2, v14, v15
	v_cvt_pk_bf16_f32 v3, v16, v17
	global_store_dwordx2 v[40:41], v[2:3], off offset:48
	s_branch .LBB0_421
.Lhl_exit:
	s_barrier
